# baseline (speedup 1.0000x reference)
; __device__ __forceinline__ int crow(int r, int hi) { return (r & 3) + 8 * (r >> 2) + 4 * hi; }
; __device__ __forceinline__ void partialSM(f32x16& p0, f32x16& p1, float& m_reg, float& mn, float& alpha) {
;     ...
;   if (__builtin_expect(__all(pmax - m_reg <= THR / SCALE), 1)) { mn = m_reg; alpha = 1.f; }
;   else { mn = fmaxf(m_reg, pmax); alpha = __builtin_amdgcn_exp2f((m_reg - mn) * C); m_reg = mn; }
; __device__ __forceinline__ void na_items(const Params& p, int l, int L, char* shm, const int tid, const int local, const int G, const int nNA) {
;     ...
;         if (__any(alpha < 1.f)) {
;           if (hi == 0) wsf[r32] = alpha;
;           asm volatile("s_waitcnt lgkmcnt(0)" ::: "memory");
; #pragma unroll
;           for (int r = 0; r < 16; ++r) { const float a = wsf[crow(r, hi)]; o0[r] *= a; o1[r] *= a; }
;         }
.LBB0_447:
	s_and_b32 s97, s42, 1
	s_add_i32 s6, s99, s42
	s_cmp_ge_i32 s6, s46
	s_cselect_b64 s[42:43], -1, 0
	s_cmp_lt_i32 s6, s98
	s_cselect_b64 vcc, -1, 0
	s_and_b64 s[42:43], s[42:43], vcc
	s_andn2_b64 vcc, exec, s[42:43]
	s_cbranch_vccnz .LBB0_517
	s_lshl_b32 s6, s97, 13
	v_add_u32_e32 v236, s6, v109
	v_add_u32_e32 v237, s6, v120
	v_add_u32_e32 v240, s6, v121
	v_add_u32_e32 v241, s6, v122
	s_cmp_eq_u64 s[40:41], 0
	s_cbranch_scc1 .Lna_left
	ds_read_b128 v[220:223], v236
	ds_read_b128 v[224:227], v236 offset:4096
	ds_read_b128 v[228:231], v237
	ds_read_b128 v[232:235], v237 offset:4096
	ds_read2_b32 v[212:213], v117 offset0:24 offset1:25
	ds_read2_b32 v[214:215], v117 offset0:26 offset1:27
	ds_read2_b32 v[2:3], v117 offset0:32 offset1:33
	ds_read2_b32 v[4:5], v117 offset0:34 offset1:35
	ds_read2_b32 v[6:7], v117 offset0:40 offset1:41
	ds_read2_b32 v[8:9], v117 offset0:42 offset1:43
	ds_read2_b32 v[10:11], v117 offset0:48 offset1:49
	ds_read2_b32 v[12:13], v117 offset0:50 offset1:51
	ds_read2_b32 v[250:251], v117 offset0:56 offset1:57
	ds_read2_b32 v[252:253], v117 offset0:58 offset1:59
	v_mov_b32_e32 v244, 0xf149f2ca
	s_waitcnt lgkmcnt(13)
	v_mfma_f32_32x32x16_bf16 v[64:79], v[220:223], v[80:83], 0
	ds_read_b128 v[220:223], v240
	s_waitcnt lgkmcnt(13)
	v_mfma_f32_32x32x16_bf16 v[48:63], v[224:227], v[80:83], 0
	ds_read_b128 v[224:227], v240 offset:4096
	s_waitcnt lgkmcnt(13)
	v_mfma_f32_32x32x16_bf16 v[64:79], v[228:231], v[84:87], v[64:79]
	ds_read_b128 v[228:231], v241
	s_waitcnt lgkmcnt(13)
	v_mfma_f32_32x32x16_bf16 v[48:63], v[232:235], v[84:87], v[48:63]
	ds_read_b128 v[232:235], v241 offset:4096
	s_waitcnt lgkmcnt(3)
	v_mfma_f32_32x32x16_bf16 v[64:79], v[220:223], v[88:91], v[64:79]
	s_waitcnt lgkmcnt(2)
	v_mfma_f32_32x32x16_bf16 v[48:63], v[224:227], v[88:91], v[48:63]
	s_waitcnt lgkmcnt(1)
	v_mfma_f32_32x32x16_bf16 v[64:79], v[228:231], v[92:95], v[64:79]
	s_waitcnt lgkmcnt(0)
	v_mfma_f32_32x32x16_bf16 v[48:63], v[232:235], v[92:95], v[48:63]
	s_nop 9
	v_add_f32_e32 v76, v76, v212
	v_add_f32_e32 v77, v77, v213
	v_add_f32_e32 v78, v78, v214
	v_add_f32_e32 v79, v79, v215
	v_cndmask_b32_e64 v76, v244, v76, s[78:79]
	v_cndmask_b32_e64 v77, v244, v77, s[0:1]
	v_cndmask_b32_e64 v78, v244, v78, s[70:71]
	v_cndmask_b32_e64 v79, v244, v79, s[2:3]
	v_add_f32_e32 v48, v48, v2
	v_add_f32_e32 v49, v49, v3
	v_add_f32_e32 v50, v50, v4
	v_add_f32_e32 v51, v51, v5
	v_add_f32_e32 v52, v52, v6
	v_add_f32_e32 v53, v53, v7
	v_add_f32_e32 v54, v54, v8
	v_add_f32_e32 v55, v55, v9
	v_add_f32_e32 v56, v56, v10
	v_add_f32_e32 v57, v57, v11
	v_add_f32_e32 v58, v58, v12
	v_add_f32_e32 v59, v59, v13
	v_add_f32_e32 v60, v60, v250
	v_add_f32_e32 v61, v61, v251
	v_add_f32_e32 v62, v62, v252
	v_add_f32_e32 v63, v63, v253
	ds_read_b128 v[2:5], v237 offset:16384
	ds_read_b128 v[6:9], v237 offset:20480
	ds_read_b128 v[10:13], v240 offset:16384
	ds_read_b128 v[250:253], v240 offset:20480
	v_cndmask_b32_e64 v48, v244, v48, s[90:91]
	v_cndmask_b32_e64 v49, v244, v49, s[94:95]
	v_cndmask_b32_e64 v50, v244, v50, s[44:45]
	v_cndmask_b32_e64 v51, v244, v51, s[84:85]
	v_cndmask_b32_e64 v52, v244, v52, s[86:87]
	v_cndmask_b32_e64 v53, v244, v53, s[56:57]
	v_cndmask_b32_e64 v54, v244, v54, s[62:63]
	v_cndmask_b32_e64 v55, v244, v55, s[64:65]
	v_cndmask_b32_e64 v56, v244, v56, s[24:25]
	v_cndmask_b32_e64 v57, v244, v57, s[26:27]
	v_cndmask_b32_e64 v58, v244, v58, s[28:29]
	v_cndmask_b32_e64 v59, v244, v59, s[30:31]
	v_cndmask_b32_e64 v60, v244, v60, s[34:35]
	v_cndmask_b32_e64 v61, v244, v61, s[36:37]
	v_cndmask_b32_e64 v62, v244, v62, s[38:39]
	v_cndmask_b32_e64 v63, v244, v63, s[40:41]
	v_max3_f32 v245, v76, v77, v78
	v_max3_f32 v245, v245, v79, v48
	v_max3_f32 v245, v245, v49, v50
	v_max3_f32 v245, v245, v51, v52
	v_max3_f32 v245, v245, v53, v54
	v_max3_f32 v245, v245, v55, v56
	v_max3_f32 v245, v245, v57, v58
	v_max3_f32 v245, v245, v59, v60
	v_max3_f32 v245, v245, v61, v62
	v_max_f32_e32 v245, v245, v63
	v_mov_b32_e32 v238, v245
	s_nop 1
	v_permlane32_swap_b32_e32 v245, v238
	v_max_f32_e32 v245, v245, v238
	v_sub_f32_e32 v238, v245, v210
	s_mov_b32 s6, 0x42800000
	v_cmp_ge_f32_e32 vcc, s6, v238
	v_max_f32_e32 v238, v210, v245
	v_sub_f32_e32 v243, v210, v238
	v_mul_f32_e32 v243, 0x3e38aa3b, v243
	v_exp_f32_e32 v243, v243
	s_cmp_eq_u64 vcc, exec
	s_cselect_b64 s[42:43], -1, 0
	v_cndmask_b32_e64 v243, v243, 1.0, s[42:43]
	s_cbranch_scc1 .Lna_norescale_R
	s_and_saveexec_b64 vcc, s[4:5]
	ds_write_b32 v170, v243 offset:32768
	s_or_b64 exec, exec, vcc
	s_waitcnt lgkmcnt(0)
	v_add_u32_e32 v0, s82, v108
	ds_read_b128 v[220:223], v0 offset:32864
	ds_read_b128 v[224:227], v0 offset:32832
	ds_read_b128 v[228:231], v0 offset:32800
	ds_read_b128 v[232:235], v0 offset:32768
	s_waitcnt lgkmcnt(0)
	v_pk_mul_f32 v[28:29], v[28:29], v[220:221]
	v_pk_mul_f32 v[30:31], v[30:31], v[222:223]
	v_pk_mul_f32 v[24:25], v[24:25], v[224:225]
	v_pk_mul_f32 v[26:27], v[26:27], v[226:227]
	v_pk_mul_f32 v[20:21], v[20:21], v[228:229]
	v_pk_mul_f32 v[22:23], v[22:23], v[230:231]
	v_pk_mul_f32 v[16:17], v[16:17], v[232:233]
	v_pk_mul_f32 v[18:19], v[18:19], v[234:235]
	v_pk_mul_f32 v[44:45], v[44:45], v[220:221]
	v_pk_mul_f32 v[46:47], v[46:47], v[222:223]
	v_pk_mul_f32 v[40:41], v[40:41], v[224:225]
	v_pk_mul_f32 v[42:43], v[42:43], v[226:227]
	v_pk_mul_f32 v[36:37], v[36:37], v[228:229]
	v_pk_mul_f32 v[38:39], v[38:39], v[230:231]
	v_pk_mul_f32 v[32:33], v[32:33], v[232:233]
	v_pk_mul_f32 v[34:35], v[34:35], v[234:235]

; __device__ __forceinline__ int crow(int r, int hi) { return (r & 3) + 8 * (r >> 2) + 4 * hi; }
; __device__ __forceinline__ void partialSM(f32x16& p0, f32x16& p1, float& m_reg, float& mn, float& alpha) {
;     ...
;   if (__builtin_expect(__all(pmax - m_reg <= THR / SCALE), 1)) { mn = m_reg; alpha = 1.f; }
;   else { mn = fmaxf(m_reg, pmax); alpha = __builtin_amdgcn_exp2f((m_reg - mn) * C); m_reg = mn; }
; __device__ __forceinline__ void na_items(const Params& p, int l, int L, char* shm, const int tid, const int local, const int G, const int nNA) {
;     ...
;         if (__any(alpha < 1.f)) {
;           if (hi == 0) wsf[r32] = alpha;
;           asm volatile("s_waitcnt lgkmcnt(0)" ::: "memory");
; #pragma unroll
;           for (int r = 0; r < 16; ++r) { const float a = wsf[crow(r, hi)]; o0[r] *= a; o1[r] *= a; }
;         }
.Lna_left:
	ds_read_b128 v[220:223], v236
	ds_read_b128 v[224:227], v236 offset:4096
	ds_read_b128 v[228:231], v237
	ds_read_b128 v[232:235], v237 offset:4096
	ds_read2_b32 v[2:3], v117 offset1:1
	ds_read2_b32 v[4:5], v117 offset0:2 offset1:3
	ds_read2_b32 v[6:7], v117 offset0:8 offset1:9
	ds_read2_b32 v[8:9], v117 offset0:10 offset1:11
	ds_read2_b32 v[10:11], v117 offset0:16 offset1:17
	ds_read2_b32 v[12:13], v117 offset0:18 offset1:19
	ds_read2_b32 v[250:251], v117 offset0:24 offset1:25
	ds_read2_b32 v[252:253], v117 offset0:26 offset1:27
	ds_read2_b32 v[216:217], v117 offset0:32 offset1:33
	ds_read2_b32 v[218:219], v117 offset0:34 offset1:35
	v_mov_b32_e32 v244, 0xf149f2ca
	s_waitcnt lgkmcnt(13)
	v_mfma_f32_32x32x16_bf16 v[64:79], v[220:223], v[80:83], 0
	ds_read_b128 v[220:223], v240
	s_waitcnt lgkmcnt(13)
	v_mfma_f32_32x32x16_bf16 v[48:63], v[224:227], v[80:83], 0
	ds_read_b128 v[224:227], v240 offset:4096
	s_waitcnt lgkmcnt(13)
	v_mfma_f32_32x32x16_bf16 v[64:79], v[228:231], v[84:87], v[64:79]
	ds_read_b128 v[228:231], v241
	s_waitcnt lgkmcnt(13)
	v_mfma_f32_32x32x16_bf16 v[48:63], v[232:235], v[84:87], v[48:63]
	ds_read_b128 v[232:235], v241 offset:4096
	s_waitcnt lgkmcnt(3)
	v_mfma_f32_32x32x16_bf16 v[64:79], v[220:223], v[88:91], v[64:79]
	s_waitcnt lgkmcnt(2)
	v_mfma_f32_32x32x16_bf16 v[48:63], v[224:227], v[88:91], v[48:63]
	s_waitcnt lgkmcnt(1)
	v_mfma_f32_32x32x16_bf16 v[64:79], v[228:231], v[92:95], v[64:79]
	s_waitcnt lgkmcnt(0)
	v_mfma_f32_32x32x16_bf16 v[48:63], v[232:235], v[92:95], v[48:63]
	s_nop 9
	v_add_f32_e32 v64, v64, v2
	v_add_f32_e32 v65, v65, v3
	v_add_f32_e32 v66, v66, v4
	v_add_f32_e32 v67, v67, v5
	v_add_f32_e32 v68, v68, v6
	v_add_f32_e32 v69, v69, v7
	v_add_f32_e32 v70, v70, v8
	v_add_f32_e32 v71, v71, v9
	v_add_f32_e32 v72, v72, v10
	v_add_f32_e32 v73, v73, v11
	v_add_f32_e32 v74, v74, v12
	v_add_f32_e32 v75, v75, v13
	v_add_f32_e32 v76, v76, v250
	v_add_f32_e32 v77, v77, v251
	v_add_f32_e32 v78, v78, v252
	v_add_f32_e32 v79, v79, v253
	v_cndmask_b32_e64 v64, v244, v64, s[8:9]
	v_cndmask_b32_e64 v65, v244, v65, s[10:11]
	v_cndmask_b32_e64 v66, v244, v66, s[12:13]
	v_cndmask_b32_e64 v67, v244, v67, s[14:15]
	v_cndmask_b32_e64 v68, v244, v68, s[16:17]
	v_cndmask_b32_e64 v69, v244, v69, s[18:19]
	v_cndmask_b32_e64 v70, v244, v70, s[20:21]
	v_cndmask_b32_e64 v71, v244, v71, s[22:23]
	v_cndmask_b32_e64 v72, v244, v72, s[66:67]
	v_cndmask_b32_e64 v73, v244, v73, s[68:69]
	v_cndmask_b32_e64 v74, v244, v74, s[72:73]
	v_cndmask_b32_e64 v75, v244, v75, s[74:75]
	v_cndmask_b32_e64 v76, v244, v76, s[78:79]
	v_cndmask_b32_e64 v77, v244, v77, s[0:1]
	v_cndmask_b32_e64 v78, v244, v78, s[70:71]
	v_cndmask_b32_e64 v79, v244, v79, s[2:3]
	v_add_f32_e32 v48, v48, v216
	v_add_f32_e32 v49, v49, v217
	v_add_f32_e32 v50, v50, v218
	v_add_f32_e32 v51, v51, v219
	ds_read_b128 v[2:5], v236 offset:16384
	ds_read_b128 v[6:9], v236 offset:20480
	ds_read_b128 v[10:13], v237 offset:16384
	ds_read_b128 v[250:253], v237 offset:20480
	v_cndmask_b32_e64 v48, v244, v48, s[90:91]
	v_cndmask_b32_e64 v49, v244, v49, s[94:95]
	v_cndmask_b32_e64 v50, v244, v50, s[44:45]
	v_cndmask_b32_e64 v51, v244, v51, s[84:85]
	v_max3_f32 v245, v64, v65, v66
	v_max3_f32 v245, v245, v67, v68
	v_max3_f32 v245, v245, v69, v70
	v_max3_f32 v245, v245, v71, v72
	v_max3_f32 v245, v245, v73, v74
	v_max3_f32 v245, v245, v75, v76
	v_max3_f32 v245, v245, v77, v78
	v_max3_f32 v245, v245, v79, v48
	v_max3_f32 v245, v245, v49, v50
	v_max_f32_e32 v245, v245, v51
	v_mov_b32_e32 v238, v245
	s_nop 1
	v_permlane32_swap_b32_e32 v245, v238
	v_max_f32_e32 v245, v245, v238
	v_sub_f32_e32 v238, v245, v210
	s_mov_b32 s6, 0x42800000
	v_cmp_ge_f32_e32 vcc, s6, v238
	v_max_f32_e32 v238, v210, v245
	v_sub_f32_e32 v243, v210, v238
	v_mul_f32_e32 v243, 0x3e38aa3b, v243
	v_exp_f32_e32 v243, v243
	s_cmp_eq_u64 vcc, exec
	s_cselect_b64 s[42:43], -1, 0
	v_cndmask_b32_e64 v243, v243, 1.0, s[42:43]
	s_cbranch_scc1 .Lna_norescale_L
	s_and_saveexec_b64 vcc, s[4:5]
	ds_write_b32 v170, v243 offset:32768
	s_or_b64 exec, exec, vcc
	s_waitcnt lgkmcnt(0)
	v_add_u32_e32 v0, s82, v108
	ds_read_b128 v[220:223], v0 offset:32864
	ds_read_b128 v[224:227], v0 offset:32832
	ds_read_b128 v[228:231], v0 offset:32800
	ds_read_b128 v[232:235], v0 offset:32768
	s_waitcnt lgkmcnt(0)
	v_pk_mul_f32 v[28:29], v[28:29], v[220:221]
	v_pk_mul_f32 v[30:31], v[30:31], v[222:223]
	v_pk_mul_f32 v[24:25], v[24:25], v[224:225]
	v_pk_mul_f32 v[26:27], v[26:27], v[226:227]
	v_pk_mul_f32 v[20:21], v[20:21], v[228:229]
	v_pk_mul_f32 v[22:23], v[22:23], v[230:231]
	v_pk_mul_f32 v[16:17], v[16:17], v[232:233]
	v_pk_mul_f32 v[18:19], v[18:19], v[234:235]
	v_pk_mul_f32 v[44:45], v[44:45], v[220:221]
	v_pk_mul_f32 v[46:47], v[46:47], v[222:223]
	v_pk_mul_f32 v[40:41], v[40:41], v[224:225]
	v_pk_mul_f32 v[42:43], v[42:43], v[226:227]
	v_pk_mul_f32 v[36:37], v[36:37], v[228:229]
	v_pk_mul_f32 v[38:39], v[38:39], v[230:231]
	v_pk_mul_f32 v[32:33], v[32:33], v[232:233]
	v_pk_mul_f32 v[34:35], v[34:35], v[234:235]

; #define SCHED() __builtin_amdgcn_sched_barrier(0)
; #define PART(P0, P1) do { _Pragma("unroll") for (int r = 0; r < 16; ++r) FMK(P0[r]);                             \
;     _Pragma("unroll") for (int r = 0; r < 16; ++r) FMK(P1[r]);                                                    \
;     _Pragma("unroll") for (int r = 0; r < 16; ++r) P0[r] = __builtin_amdgcn_exp2f(P0[r]); } while (0)
; #define EXP1(P1) do { _Pragma("unroll") for (int r = 0; r < 16; ++r) P1[r] = __builtin_amdgcn_exp2f(P1[r]); } while (0)
; #define PACK(P0, P1) do { float ps_ = 0.f; _Pragma("unroll") for (int r = 0; r < 16; ++r) ps_ += P0[r] + P1[r]; lsum += ps_;  \
;     PK4(P0, 0, pa0); PK4(P0, 8, pa1); PK4(P1, 0, pa2); PK4(P1, 8, pa3); } while (0)
; #define VFR(slot) do { const char* Vc = shm + (slot) * 16384 + 8192;                                               \
;     _Pragma("unroll") for (int ks = 0; ks < 4; ++ks) { fr_[ks * 2] = *(const bf16x8*)(Vc + roff[ks]); fr_[ks * 2 + 1] = *(const bf16x8*)(Vc + roff[ks] + 4096); } } while (0)
; #define QKT(P0, P1) do { _Pragma("unroll") for (int r = 0; r < 16; ++r) { P0[r] = 0.f; P1[r] = 0.f; }              \
;     _Pragma("unroll") for (int d0 = 0; d0 < 4; ++d0) { P0 = __builtin_amdgcn_mfma_f32_32x32x16_bf16(fr_[d0 * 2], qr[d0], P0, 0, 0, 0);     \
;       P1 = __builtin_amdgcn_mfma_f32_32x32x16_bf16(fr_[d0 * 2 + 1], qr[d0], P1, 0, 0, 0); } } while (0)
; #define PVM() do { PV1(pa0, 0); PV1(pa1, 1); PV1(pa2, 2); PV1(pa3, 3); } while (0)
; __device__ __forceinline__ void gqa_items(const Params& p, int l, int L, char* shm, const int tid, const int local, const int G, const int nGQ) {
;     ...
;       QKT(pA0, pA1); SCHED();
;       PART(pA0, pA1); EXP1(pA1); SCHED();
;       VFR(cur); SCHED();
;       PACK(pA0, pA1); SCHED();
;       PVM();
.Lgq_nold:
	s_waitcnt lgkmcnt(7)
	v_mfma_f32_32x32x16_bf16 v[34:49], v[192:195], v[50:53], 0
	ds_read_b128 v[144:147], v224 offset:8192
	s_waitcnt lgkmcnt(7)
	v_mfma_f32_32x32x16_bf16 v[128:143], v[196:199], v[50:53], 0
	ds_read_b128 v[148:151], v224 offset:12288
	s_waitcnt lgkmcnt(7)
	v_mfma_f32_32x32x16_bf16 v[34:49], v[200:203], v[54:57], v[34:49]
	ds_read_b128 v[152:155], v225 offset:8192
	s_waitcnt lgkmcnt(7)
	v_mfma_f32_32x32x16_bf16 v[128:143], v[204:207], v[54:57], v[128:143]
	ds_read_b128 v[156:159], v225 offset:12288
	s_waitcnt lgkmcnt(7)
	v_mfma_f32_32x32x16_bf16 v[34:49], v[208:211], v[58:61], v[34:49]
	ds_read_b128 v[160:163], v226 offset:8192
	s_waitcnt lgkmcnt(7)
	v_mfma_f32_32x32x16_bf16 v[128:143], v[212:215], v[58:61], v[128:143]
	ds_read_b128 v[164:167], v226 offset:12288
	s_waitcnt lgkmcnt(7)
	v_mfma_f32_32x32x16_bf16 v[34:49], v[216:219], v[62:65], v[34:49]
	ds_read_b128 v[168:171], v227 offset:8192
	s_waitcnt lgkmcnt(7)
	v_mfma_f32_32x32x16_bf16 v[128:143], v[220:223], v[62:65], v[128:143]
	ds_read_b128 v[172:175], v227 offset:12288
	s_add_i32 s3, s14, 1
	s_and_b32 s3, s3, 3
	s_lshl_b32 s3, s3, 14
	v_add_u32_e32 v230, s3, v109
	v_add_u32_e32 v231, s3, v120
	v_add_u32_e32 v232, s3, v121
	v_add_u32_e32 v233, s3, v122
	s_waitcnt lgkmcnt(4)
	ds_read_b128 v[192:195], v230
	ds_read_b128 v[196:199], v230 offset:4096
	ds_read_b128 v[200:203], v231
	ds_read_b128 v[204:207], v231 offset:4096
	ds_read_b128 v[208:211], v232
	ds_read_b128 v[212:215], v232 offset:4096
	ds_read_b128 v[216:219], v233
	ds_read_b128 v[220:223], v233 offset:4096
	v_fmamk_f32 v34, v34, 0x3e38aa3b, v71
	v_fmamk_f32 v35, v35, 0x3e38aa3b, v71
	v_fmamk_f32 v36, v36, 0x3e38aa3b, v71
	v_fmamk_f32 v37, v37, 0x3e38aa3b, v71
	v_fmamk_f32 v38, v38, 0x3e38aa3b, v71
	v_fmamk_f32 v39, v39, 0x3e38aa3b, v71
	v_fmamk_f32 v40, v40, 0x3e38aa3b, v71
	v_fmamk_f32 v41, v41, 0x3e38aa3b, v71
	v_fmamk_f32 v42, v42, 0x3e38aa3b, v71
	v_fmamk_f32 v43, v43, 0x3e38aa3b, v71
	v_fmamk_f32 v44, v44, 0x3e38aa3b, v71
	v_fmamk_f32 v45, v45, 0x3e38aa3b, v71
	v_fmamk_f32 v46, v46, 0x3e38aa3b, v71
	v_fmamk_f32 v47, v47, 0x3e38aa3b, v71
	v_fmamk_f32 v48, v48, 0x3e38aa3b, v71
	v_fmamk_f32 v49, v49, 0x3e38aa3b, v71
	v_exp_f32_e32 v34, v34
	v_exp_f32_e32 v35, v35
	v_exp_f32_e32 v36, v36
	v_exp_f32_e32 v37, v37
	v_exp_f32_e32 v38, v38
	v_exp_f32_e32 v39, v39
	v_exp_f32_e32 v40, v40
	v_exp_f32_e32 v41, v41
	v_exp_f32_e32 v42, v42
	v_exp_f32_e32 v43, v43
	v_exp_f32_e32 v44, v44
	v_exp_f32_e32 v45, v45
	v_exp_f32_e32 v46, v46
	v_exp_f32_e32 v47, v47
	v_exp_f32_e32 v48, v48
	v_exp_f32_e32 v49, v49
	v_cvt_pk_bf16_f32 v176, v34, v35
	v_cvt_pk_bf16_f32 v177, v36, v37
	v_cvt_pk_bf16_f32 v178, v38, v39
	v_cvt_pk_bf16_f32 v179, v40, v41
	v_cvt_pk_bf16_f32 v180, v42, v43
	v_cvt_pk_bf16_f32 v181, v44, v45
	v_cvt_pk_bf16_f32 v182, v46, v47
	v_cvt_pk_bf16_f32 v183, v48, v49
	v_permlane32_swap_b32_e32 v176, v178
	v_permlane32_swap_b32_e32 v177, v179
	v_permlane32_swap_b32_e32 v180, v182
	v_permlane32_swap_b32_e32 v181, v183
	s_waitcnt lgkmcnt(8)
	v_mfma_f32_32x32x16_bf16 v[18:33], v[176:179], v[144:147], v[18:33]
	v_fmamk_f32 v128, v128, 0x3e38aa3b, v71
	v_fmamk_f32 v129, v129, 0x3e38aa3b, v71
	v_fmamk_f32 v130, v130, 0x3e38aa3b, v71
	v_fmamk_f32 v131, v131, 0x3e38aa3b, v71
	v_fmamk_f32 v132, v132, 0x3e38aa3b, v71
	v_fmamk_f32 v133, v133, 0x3e38aa3b, v71
	v_fmamk_f32 v134, v134, 0x3e38aa3b, v71
	v_fmamk_f32 v135, v135, 0x3e38aa3b, v71
	v_mfma_f32_32x32x16_bf16 v[2:17], v[176:179], v[148:151], v[2:17]
	v_fmamk_f32 v136, v136, 0x3e38aa3b, v71
	v_fmamk_f32 v137, v137, 0x3e38aa3b, v71
	v_fmamk_f32 v138, v138, 0x3e38aa3b, v71
	v_fmamk_f32 v139, v139, 0x3e38aa3b, v71
	v_fmamk_f32 v140, v140, 0x3e38aa3b, v71
	v_fmamk_f32 v141, v141, 0x3e38aa3b, v71
	v_fmamk_f32 v142, v142, 0x3e38aa3b, v71
	v_fmamk_f32 v143, v143, 0x3e38aa3b, v71
	v_mfma_f32_32x32x16_bf16 v[18:33], v[180:183], v[152:155], v[18:33]
	v_exp_f32_e32 v128, v128
	v_exp_f32_e32 v129, v129
	v_exp_f32_e32 v130, v130
	v_exp_f32_e32 v131, v131
	v_exp_f32_e32 v132, v132
	v_exp_f32_e32 v133, v133
	v_exp_f32_e32 v134, v134
	v_exp_f32_e32 v135, v135
	v_mfma_f32_32x32x16_bf16 v[2:17], v[180:183], v[156:159], v[2:17]
	v_exp_f32_e32 v136, v136
	v_exp_f32_e32 v137, v137
	v_exp_f32_e32 v138, v138
	v_exp_f32_e32 v139, v139
	v_exp_f32_e32 v140, v140
	v_exp_f32_e32 v141, v141
	v_exp_f32_e32 v142, v142
	v_exp_f32_e32 v143, v143
	v_cvt_pk_bf16_f32 v184, v128, v129
	v_cvt_pk_bf16_f32 v185, v130, v131
	v_cvt_pk_bf16_f32 v186, v132, v133
	v_cvt_pk_bf16_f32 v187, v134, v135
	v_cvt_pk_bf16_f32 v188, v136, v137
	v_cvt_pk_bf16_f32 v189, v138, v139
	v_cvt_pk_bf16_f32 v190, v140, v141
	v_cvt_pk_bf16_f32 v191, v142, v143
	v_permlane32_swap_b32_e32 v184, v186
	v_permlane32_swap_b32_e32 v185, v187
	v_permlane32_swap_b32_e32 v188, v190
	v_permlane32_swap_b32_e32 v189, v191
	v_add_f32_e32 v34, v34, v128
	v_add_f32_e32 v35, v35, v129
	v_mfma_f32_32x32x16_bf16 v[18:33], v[184:187], v[160:163], v[18:33]
	v_add_f32_e32 v36, v36, v130
	v_add_f32_e32 v37, v37, v131
	v_add_f32_e32 v38, v38, v132
	v_add_f32_e32 v39, v39, v133
	v_add_f32_e32 v40, v40, v134
	v_add_f32_e32 v41, v41, v135
	v_add_f32_e32 v42, v42, v136
	v_add_f32_e32 v43, v43, v137
	v_mfma_f32_32x32x16_bf16 v[2:17], v[184:187], v[164:167], v[2:17]
	v_add_f32_e32 v44, v44, v138
	v_add_f32_e32 v45, v45, v139
	v_add_f32_e32 v46, v46, v140
	v_add_f32_e32 v47, v47, v141
	v_add_f32_e32 v48, v48, v142
	v_add_f32_e32 v49, v49, v143
	v_add_f32_e32 v35, v35, v34
	v_add_f32_e32 v36, v36, v35
	v_mfma_f32_32x32x16_bf16 v[18:33], v[188:191], v[168:171], v[18:33]
	v_add_f32_e32 v37, v37, v36
	v_add_f32_e32 v38, v38, v37
	v_add_f32_e32 v39, v39, v38
	v_add_f32_e32 v40, v40, v39
	v_add_f32_e32 v41, v41, v40
	v_add_f32_e32 v42, v42, v41
	v_add_f32_e32 v43, v43, v42
	v_add_f32_e32 v44, v44, v43
	v_mfma_f32_32x32x16_bf16 v[2:17], v[188:191], v[172:175], v[2:17]
	v_add_f32_e32 v45, v45, v44
	v_add_f32_e32 v46, v46, v45
	v_add_f32_e32 v47, v47, v46
	v_add_f32_e32 v48, v48, v47
	v_add_f32_e32 v49, v49, v48
	v_add_f32_e32 v127, v127, v49
	s_waitcnt lgkmcnt(0)
; #define SCHED() __builtin_amdgcn_sched_barrier(0)
; #define PART(P0, P1) do { _Pragma("unroll") for (int r = 0; r < 16; ++r) FMK(P0[r]);                             \
;     _Pragma("unroll") for (int r = 0; r < 16; ++r) FMK(P1[r]);                                                    \
;     _Pragma("unroll") for (int r = 0; r < 16; ++r) P0[r] = __builtin_amdgcn_exp2f(P0[r]); } while (0)
; #define EXP1(P1) do { _Pragma("unroll") for (int r = 0; r < 16; ++r) P1[r] = __builtin_amdgcn_exp2f(P1[r]); } while (0)
; #define PACK(P0, P1) do { float ps_ = 0.f; _Pragma("unroll") for (int r = 0; r < 16; ++r) ps_ += P0[r] + P1[r]; lsum += ps_;  \
;     PK4(P0, 0, pa0); PK4(P0, 8, pa1); PK4(P1, 0, pa2); PK4(P1, 8, pa3); } while (0)
; #define VFR(slot) do { const char* Vc = shm + (slot) * 16384 + 8192;                                               \
;     _Pragma("unroll") for (int ks = 0; ks < 4; ++ks) { fr_[ks * 2] = *(const bf16x8*)(Vc + roff[ks]); fr_[ks * 2 + 1] = *(const bf16x8*)(Vc + roff[ks] + 4096); } } while (0)
; #define QKT(P0, P1) do { _Pragma("unroll") for (int r = 0; r < 16; ++r) { P0[r] = 0.f; P1[r] = 0.f; }              \
;     _Pragma("unroll") for (int d0 = 0; d0 < 4; ++d0) { P0 = __builtin_amdgcn_mfma_f32_32x32x16_bf16(fr_[d0 * 2], qr[d0], P0, 0, 0, 0);     \
;       P1 = __builtin_amdgcn_mfma_f32_32x32x16_bf16(fr_[d0 * 2 + 1], qr[d0], P1, 0, 0, 0); } } while (0)
; #define PVM() do { PV1(pa0, 0); PV1(pa1, 1); PV1(pa2, 2); PV1(pa3, 3); } while (0)
; __device__ __forceinline__ void gqa_items(const Params& p, int l, int L, char* shm, const int tid, const int local, const int G, const int nGQ) {
;     ...
;       QKT(pA0, pA1); SCHED();
;       PART(pA0, pA1); EXP1(pA1); SCHED();
;       VFR(cur); SCHED();
;       PACK(pA0, pA1); SCHED();
;       PVM();
;       SCHED();
;       if (j + 2 < NT) asm volatile("s_waitcnt vmcnt(2) lgkmcnt(0)" ::: "memory"); else asm volatile("s_waitcnt vmcnt(0) lgkmcnt(0)" ::: "memory");
;       __builtin_amdgcn_s_barrier(); asm volatile("" ::: "memory"); SCHED();
;       cur = (cur == 2) ? 0 : cur + 1;
;     }
	v_mfma_f32_32x32x16_bf16 v[34:49], v[192:195], v[50:53], 0
	ds_read_b128 v[144:147], v230 offset:8192
	v_mfma_f32_32x32x16_bf16 v[128:143], v[196:199], v[50:53], 0
	ds_read_b128 v[148:151], v230 offset:12288
	v_mfma_f32_32x32x16_bf16 v[34:49], v[200:203], v[54:57], v[34:49]
	ds_read_b128 v[152:155], v231 offset:8192
	v_mfma_f32_32x32x16_bf16 v[128:143], v[204:207], v[54:57], v[128:143]
	ds_read_b128 v[156:159], v231 offset:12288
	v_mfma_f32_32x32x16_bf16 v[34:49], v[208:211], v[58:61], v[34:49]
	ds_read_b128 v[160:163], v232 offset:8192
	v_mfma_f32_32x32x16_bf16 v[128:143], v[212:215], v[58:61], v[128:143]
	ds_read_b128 v[164:167], v232 offset:12288
	v_mfma_f32_32x32x16_bf16 v[34:49], v[216:219], v[62:65], v[34:49]
	ds_read_b128 v[168:171], v233 offset:8192
	v_mfma_f32_32x32x16_bf16 v[128:143], v[220:223], v[62:65], v[128:143]
	ds_read_b128 v[172:175], v233 offset:12288
	s_add_i32 s0, s14, 2
	s_and_b32 s0, s0, 3
	s_lshl_b32 s16, s0, 14
	v_add_u32_e32 v224, s16, v109
	v_add_u32_e32 v225, s16, v120
	v_add_u32_e32 v226, s16, v121
	v_add_u32_e32 v227, s16, v122
	s_nop 1
	v_fmamk_f32 v34, v34, 0x3e38aa3b, v71
	v_fmamk_f32 v35, v35, 0x3e38aa3b, v71
	v_fmamk_f32 v36, v36, 0x3e38aa3b, v71
	v_fmamk_f32 v37, v37, 0x3e38aa3b, v71
	v_fmamk_f32 v38, v38, 0x3e38aa3b, v71
	v_fmamk_f32 v39, v39, 0x3e38aa3b, v71
	v_fmamk_f32 v40, v40, 0x3e38aa3b, v71
	v_fmamk_f32 v41, v41, 0x3e38aa3b, v71
	v_fmamk_f32 v42, v42, 0x3e38aa3b, v71
	v_fmamk_f32 v43, v43, 0x3e38aa3b, v71
	v_fmamk_f32 v44, v44, 0x3e38aa3b, v71
	v_fmamk_f32 v45, v45, 0x3e38aa3b, v71
	v_fmamk_f32 v46, v46, 0x3e38aa3b, v71
	v_fmamk_f32 v47, v47, 0x3e38aa3b, v71
	v_fmamk_f32 v48, v48, 0x3e38aa3b, v71
	v_fmamk_f32 v49, v49, 0x3e38aa3b, v71
	v_exp_f32_e32 v34, v34
	v_exp_f32_e32 v35, v35
	v_exp_f32_e32 v36, v36
	v_exp_f32_e32 v37, v37
	v_exp_f32_e32 v38, v38
	v_exp_f32_e32 v39, v39
	v_exp_f32_e32 v40, v40
	v_exp_f32_e32 v41, v41
	v_exp_f32_e32 v42, v42
	v_exp_f32_e32 v43, v43
	v_exp_f32_e32 v44, v44
	v_exp_f32_e32 v45, v45
	v_exp_f32_e32 v46, v46
	v_exp_f32_e32 v47, v47
	v_exp_f32_e32 v48, v48
	v_exp_f32_e32 v49, v49
	v_cvt_pk_bf16_f32 v176, v34, v35
	v_cvt_pk_bf16_f32 v177, v36, v37
	v_cvt_pk_bf16_f32 v178, v38, v39
	v_cvt_pk_bf16_f32 v179, v40, v41
	v_cvt_pk_bf16_f32 v180, v42, v43
	v_cvt_pk_bf16_f32 v181, v44, v45
	v_cvt_pk_bf16_f32 v182, v46, v47
	v_cvt_pk_bf16_f32 v183, v48, v49
	v_permlane32_swap_b32_e32 v176, v178
	v_permlane32_swap_b32_e32 v177, v179
	v_permlane32_swap_b32_e32 v180, v182
	v_permlane32_swap_b32_e32 v181, v183
	s_waitcnt lgkmcnt(0)
	v_mfma_f32_32x32x16_bf16 v[18:33], v[176:179], v[144:147], v[18:33]
	v_fmamk_f32 v128, v128, 0x3e38aa3b, v71
	v_fmamk_f32 v129, v129, 0x3e38aa3b, v71
	v_fmamk_f32 v130, v130, 0x3e38aa3b, v71
	v_fmamk_f32 v131, v131, 0x3e38aa3b, v71
	v_fmamk_f32 v132, v132, 0x3e38aa3b, v71
	v_fmamk_f32 v133, v133, 0x3e38aa3b, v71
	v_fmamk_f32 v134, v134, 0x3e38aa3b, v71
	v_fmamk_f32 v135, v135, 0x3e38aa3b, v71
	v_mfma_f32_32x32x16_bf16 v[2:17], v[176:179], v[148:151], v[2:17]
	v_fmamk_f32 v136, v136, 0x3e38aa3b, v71
	v_fmamk_f32 v137, v137, 0x3e38aa3b, v71
	v_fmamk_f32 v138, v138, 0x3e38aa3b, v71
	v_fmamk_f32 v139, v139, 0x3e38aa3b, v71
	v_fmamk_f32 v140, v140, 0x3e38aa3b, v71
	v_fmamk_f32 v141, v141, 0x3e38aa3b, v71
	v_fmamk_f32 v142, v142, 0x3e38aa3b, v71
	v_fmamk_f32 v143, v143, 0x3e38aa3b, v71
	v_mfma_f32_32x32x16_bf16 v[18:33], v[180:183], v[152:155], v[18:33]
	v_exp_f32_e32 v128, v128
	v_exp_f32_e32 v129, v129
	v_exp_f32_e32 v130, v130
	v_exp_f32_e32 v131, v131
	v_exp_f32_e32 v132, v132
	v_exp_f32_e32 v133, v133
	v_exp_f32_e32 v134, v134
	v_exp_f32_e32 v135, v135
	v_mfma_f32_32x32x16_bf16 v[2:17], v[180:183], v[156:159], v[2:17]
	v_exp_f32_e32 v136, v136
	v_exp_f32_e32 v137, v137
	v_exp_f32_e32 v138, v138
	v_exp_f32_e32 v139, v139
	v_exp_f32_e32 v140, v140
	v_exp_f32_e32 v141, v141
	v_exp_f32_e32 v142, v142
	v_exp_f32_e32 v143, v143
	v_cvt_pk_bf16_f32 v184, v128, v129
	v_cvt_pk_bf16_f32 v185, v130, v131
	v_cvt_pk_bf16_f32 v186, v132, v133
	v_cvt_pk_bf16_f32 v187, v134, v135
	v_cvt_pk_bf16_f32 v188, v136, v137
	v_cvt_pk_bf16_f32 v189, v138, v139
	v_cvt_pk_bf16_f32 v190, v140, v141
	v_cvt_pk_bf16_f32 v191, v142, v143
	v_permlane32_swap_b32_e32 v184, v186
	v_permlane32_swap_b32_e32 v185, v187
	v_permlane32_swap_b32_e32 v188, v190
	v_permlane32_swap_b32_e32 v189, v191
	v_add_f32_e32 v34, v34, v128
	v_add_f32_e32 v35, v35, v129
	v_mfma_f32_32x32x16_bf16 v[18:33], v[184:187], v[160:163], v[18:33]
	v_add_f32_e32 v36, v36, v130
	v_add_f32_e32 v37, v37, v131
	v_add_f32_e32 v38, v38, v132
	v_add_f32_e32 v39, v39, v133
	v_add_f32_e32 v40, v40, v134
	v_add_f32_e32 v41, v41, v135
	v_add_f32_e32 v42, v42, v136
	v_add_f32_e32 v43, v43, v137
	v_mfma_f32_32x32x16_bf16 v[2:17], v[184:187], v[164:167], v[2:17]
	v_add_f32_e32 v44, v44, v138
	v_add_f32_e32 v45, v45, v139
	v_add_f32_e32 v46, v46, v140
	v_add_f32_e32 v47, v47, v141
	v_add_f32_e32 v48, v48, v142
	v_add_f32_e32 v49, v49, v143
	v_add_f32_e32 v35, v35, v34
	v_add_f32_e32 v36, v36, v35
	v_mfma_f32_32x32x16_bf16 v[18:33], v[188:191], v[168:171], v[18:33]
	v_add_f32_e32 v37, v37, v36
	v_add_f32_e32 v38, v38, v37
	v_add_f32_e32 v39, v39, v38
	v_add_f32_e32 v40, v40, v39
	v_add_f32_e32 v41, v41, v40
	v_add_f32_e32 v42, v42, v41
	v_add_f32_e32 v43, v43, v42
	v_add_f32_e32 v44, v44, v43
	v_mfma_f32_32x32x16_bf16 v[2:17], v[188:191], v[172:175], v[2:17]
	v_add_f32_e32 v45, v45, v44
	v_add_f32_e32 v46, v46, v45
	v_add_f32_e32 v47, v47, v46
	v_add_f32_e32 v48, v48, v47
	v_add_f32_e32 v49, v49, v48
	v_add_f32_e32 v127, v127, v49
	s_mov_b32 s14, s0
	s_add_i32 s15, s15, 2
	s_cmp_lt_u32 s15, s96
	s_waitcnt vmcnt(0) lgkmcnt(0)
	s_barrier
	s_cbranch_scc1 .Lgq_step
